# VH2: all 8 V-fragment ds_read_b64_tr hoisted above the exp/rcp chain (first fragment renamed to v[244:247])
# baseline (speedup 1.0000x reference)
.LBB0_651:
	s_max_i32 s0, s14, 0
	s_mov_b32 s6, s14
	s_add_i32 s14, s0, -1
	s_lshl_b32 s0, s14, 5
	s_add_i32 s0, s23, s0
	s_cmp_gt_i32 s6, 0
	s_waitcnt vmcnt(0)
	s_cselect_b32 s0, s0, 0x8002
	s_waitcnt lgkmcnt(0)
	v_or_b32_e32 v2, s0, v135
	v_ashrrev_i32_e32 v3, 31, v2
	v_lshlrev_b64 v[2:3], 11, v[2:3]
	ds_write_b128 v167, v[108:111]
	ds_write_b128 v167, v[104:107] offset:144
	ds_write_b128 v167, v[100:103] offset:288
	ds_write_b128 v167, v[96:99] offset:432
	ds_write_b128 v168, v[92:95] offset:4608
	ds_write_b128 v168, v[88:91] offset:4800
	ds_write_b128 v168, v[84:87] offset:4992
	ds_write_b128 v168, v[80:83] offset:5184
	v_lshl_or_b32 v2, v158, 1, v2
	v_lshl_add_u64 v[4:5], s[24:25], 0, v[2:3]
	v_lshl_add_u64 v[2:3], s[26:27], 0, v[2:3]
	global_load_dwordx4 v[108:111], v[4:5], off offset:-4096
	global_load_dwordx4 v[104:107], v[4:5], off offset:-2048
	global_load_dwordx4 v[100:103], v[4:5], off
	global_load_dwordx4 v[96:99], v[4:5], off offset:2048
	global_load_dwordx4 v[92:95], v[2:3], off offset:-4096
	global_load_dwordx4 v[88:91], v[2:3], off offset:-2048
	global_load_dwordx4 v[84:87], v[2:3], off
	global_load_dwordx4 v[80:83], v[2:3], off offset:2048
	ds_read_b128 v[128:131], v169
	ds_read_b128 v[10:13], v169 offset:32
	ds_read_b128 v[6:9], v169 offset:64
	ds_read_b128 v[2:5], v169 offset:96
	s_cmp_lt_i32 s6, 0
	s_cselect_b64 s[0:1], -1, 0
	s_cmp_gt_i32 s6, -1
	s_cselect_b64 s[2:3], -1, 0
	s_cmp_lg_u32 s6, s22
	s_cselect_b64 s[6:7], -1, 0
	s_and_b64 s[6:7], s[2:3], s[6:7]
	s_mov_b64 s[18:19], -1
	s_and_b64 vcc, exec, s[6:7]
	v_mbcnt_hi_u32_b32 v1, -1, v195
	s_mov_b64 s[6:7], -1
	s_cbranch_vccz .LBB0_653
	s_waitcnt lgkmcnt(3)
	v_mfma_f32_32x32x16_bf16 v[48:63], v[128:131], v[112:115], 0
	s_mov_b64 s[6:7], 0
	s_waitcnt lgkmcnt(2)
	v_mfma_f32_32x32x16_bf16 v[48:63], v[10:13], v[116:119], v[48:63]
	s_waitcnt lgkmcnt(1)
	v_mfma_f32_32x32x16_bf16 v[48:63], v[6:9], v[120:123], v[48:63]
	s_waitcnt lgkmcnt(0)
	v_mfma_f32_32x32x16_bf16 v[48:63], v[2:5], v[124:127], v[48:63]
	ds_read_b64_tr_b16 v[244:245], v141
	ds_read_b64_tr_b16 v[246:247], v141 offset:1536
	ds_read_b64_tr_b16 v[188:189], v141 offset:3072
	ds_read_b64_tr_b16 v[190:191], v141 offset:4608
	ds_read_b64_tr_b16 v[196:197], v141 offset:64
	ds_read_b64_tr_b16 v[198:199], v141 offset:1600
	ds_read_b64_tr_b16 v[184:185], v141 offset:3136
	ds_read_b64_tr_b16 v[186:187], v141 offset:4672
	s_nop 11
	v_exp_f32_e32 v14, v48
	v_exp_f32_e32 v15, v49
	v_exp_f32_e32 v48, v50
	v_exp_f32_e32 v49, v51
	v_exp_f32_e32 v50, v52
	v_exp_f32_e32 v51, v53
	v_exp_f32_e32 v52, v54
	v_exp_f32_e32 v53, v55
	v_exp_f32_e32 v54, v56
	v_exp_f32_e32 v55, v57
	v_exp_f32_e32 v56, v58
	v_exp_f32_e32 v57, v59
	v_exp_f32_e32 v58, v60
	v_exp_f32_e32 v59, v61
	v_exp_f32_e32 v60, v62
	v_exp_f32_e32 v61, v63
	v_pk_add_f32 v[14:15], v[14:15], 1.0 op_sel_hi:[1,0]
	v_pk_add_f32 v[48:49], v[48:49], 1.0 op_sel_hi:[1,0]
	v_pk_add_f32 v[58:59], v[58:59], 1.0 op_sel_hi:[1,0]
	v_pk_add_f32 v[50:51], v[50:51], 1.0 op_sel_hi:[1,0]
	v_pk_add_f32 v[52:53], v[52:53], 1.0 op_sel_hi:[1,0]
	v_rcp_f32_e32 v14, v14
	v_rcp_f32_e32 v15, v15
	v_rcp_f32_e32 v48, v48
	v_rcp_f32_e32 v49, v49
	v_rcp_f32_e32 v192, v58
	v_rcp_f32_e32 v193, v59
	v_pk_add_f32 v[58:59], v[60:61], 1.0 op_sel_hi:[1,0]
	v_pk_add_f32 v[54:55], v[54:55], 1.0 op_sel_hi:[1,0]
	v_pk_add_f32 v[56:57], v[56:57], 1.0 op_sel_hi:[1,0]
	v_rcp_f32_e32 v50, v50
	v_rcp_f32_e32 v51, v51
	v_rcp_f32_e32 v52, v52
	v_rcp_f32_e32 v53, v53
	v_rcp_f32_e32 v205, v59
	v_rcp_f32_e32 v68, v54
	v_rcp_f32_e32 v69, v55
	v_rcp_f32_e32 v70, v56
	v_rcp_f32_e32 v71, v57
	v_rcp_f32_e32 v204, v58
	v_pk_add_f32 v[54:55], v[14:15], 1.0 op_sel_hi:[1,0] neg_lo:[1,0] neg_hi:[1,0]
	v_pk_add_f32 v[56:57], v[48:49], 1.0 op_sel_hi:[1,0] neg_lo:[1,0] neg_hi:[1,0]
	v_pk_add_f32 v[62:63], v[50:51], 1.0 op_sel_hi:[1,0] neg_lo:[1,0] neg_hi:[1,0]
	v_pk_add_f32 v[64:65], v[52:53], 1.0 op_sel_hi:[1,0] neg_lo:[1,0] neg_hi:[1,0]
	v_pk_mul_f32 v[58:59], v[54:55], v[56:57]
	v_pk_add_f32 v[72:73], v[68:69], 1.0 op_sel_hi:[1,0] neg_lo:[1,0] neg_hi:[1,0]
	v_pk_add_f32 v[74:75], v[70:71], 1.0 op_sel_hi:[1,0] neg_lo:[1,0] neg_hi:[1,0]
	v_mul_f32_e32 v214, v58, v59
	v_pk_mul_f32 v[58:59], v[62:63], v[64:65]
	v_pk_add_f32 v[206:207], v[192:193], 1.0 op_sel_hi:[1,0] neg_lo:[1,0] neg_hi:[1,0]
	v_pk_add_f32 v[76:77], v[204:205], 1.0 op_sel_hi:[1,0] neg_lo:[1,0] neg_hi:[1,0]
	v_mul_f32_e32 v54, v58, v59
	v_pk_mul_f32 v[58:59], v[72:73], v[74:75]
	v_mov_b32_e32 v67, v54
	v_mul_f32_e32 v62, v58, v59
	v_pk_mul_f32 v[58:59], v[206:207], v[76:77]
	v_mov_b32_e32 v61, v62
	v_mul_f32_e32 v58, v58, v59
	v_mov_b32_e32 v59, v58
	v_mov_b32_e32 v215, v214
	v_permlane32_swap_b32_e32 v67, v54
	v_permlane32_swap_b32_e32 v61, v62
	v_permlane32_swap_b32_e32 v58, v59
	v_permlane32_swap_b32_e32 v214, v215
	s_nop 1
	v_mul_f32_e32 v58, v58, v59
	v_mul_f32_e32 v62, v62, v58
	v_mul_f32_e32 v61, v61, v62
	v_mul_f32_e32 v54, v54, v61
	v_mov_b32_e32 v60, v215
	v_mul_f32_e32 v66, v67, v54
	v_mul_f32_e32 v206, v60, v66
	v_cndmask_b32_e64 v60, v66, v206, s[4:5]
	v_cndmask_b32_e64 v72, 1.0, v59, s[4:5]
	v_mul_f32_e32 v59, v139, v60
	v_cndmask_b32_e64 v54, v61, v54, s[4:5]
	v_cndmask_b32_e64 v61, v58, v62, s[4:5]
	v_mul_f32_e32 v58, v57, v59
	v_mul_f32_e32 v57, v56, v58
	v_mul_f32_e32 v56, v55, v57
	v_mul_f32_e32 v55, v139, v54
	v_mul_f32_e32 v54, v65, v55
	v_pk_mul_f32 v[14:15], v[14:15], v[56:57]
	v_mul_f32_e32 v57, v64, v54
	v_mul_f32_e32 v79, v139, v61
	v_mul_f32_e32 v56, v63, v57
	v_mul_f32_e32 v78, v75, v79
	v_pk_mul_f32 v[48:49], v[48:49], v[58:59]
	v_pk_mul_f32 v[50:51], v[50:51], v[56:57]
	v_pk_mul_f32 v[52:53], v[52:53], v[54:55]
	v_cvt_pk_bf16_f32 v200, v14, v15
	v_mul_f32_e32 v15, v74, v78
	v_mul_f32_e32 v211, v139, v72
	s_waitcnt lgkmcnt(0)
	v_cvt_pk_bf16_f32 v201, v48, v49
	v_cvt_pk_bf16_f32 v202, v50, v51
	v_cvt_pk_bf16_f32 v203, v52, v53
	v_mul_f32_e32 v14, v73, v15
	v_mul_f32_e32 v210, v211, v77
	v_mfma_f32_32x32x16_bf16 v[48:63], v[244:247], v[200:203], v[32:47]
	v_mul_f32_e64 v14, v68, v14
	v_mul_f32_e64 v15, v69, v15
	v_mul_f32_e64 v208, v70, v78
	v_mul_f32_e64 v209, v71, v79
	v_mul_f32_e32 v213, v76, v210
	v_mul_f32_e32 v212, v207, v213
	v_pk_mul_f32 v[192:193], v[192:193], v[212:213]
	v_mfma_f32_32x32x16_bf16 v[64:79], v[196:199], v[200:203], v[16:31]
	v_cvt_pk_bf16_f32 v196, v14, v15
	v_mov_b32_e32 v14, v214
	v_mul_f32_e32 v14, v14, v206
	v_mul_f32_e32 v14, v139, v14
	v_mul_f32_e64 v200, v204, v210
	v_mul_f32_e64 v201, v205, v211
	v_cmp_gt_f32_e32 vcc, s21, v14
	v_cvt_pk_bf16_f32 v197, v208, v209
	v_cvt_pk_bf16_f32 v198, v192, v193
	v_cvt_pk_bf16_f32 v199, v200, v201
	s_cmp_eq_u64 vcc, exec
	s_cselect_b64 s[18:19], -1, 0
	v_mfma_f32_32x32x16_bf16 v[48:63], v[188:191], v[196:199], v[48:63]
	v_mfma_f32_32x32x16_bf16 v[64:79], v[184:187], v[196:199], v[64:79]
